# attention QK: bias tiles loaded straight into accumulator registers (swapped ds_read2 offsets), 80 v_mov + 35 waits removed per unit
# speedup vs baseline: 1.0015x; 1.0015x over previous
; #define LAS __attribute__((address_space(3)))
; __device__ __forceinline__ int crow(int r, int hi) { return (r & 3) + 8 * (r >> 2) + 4 * hi; }
; __device__ __forceinline__ void attn_phase(LAS unsigned char* lds, const bf16_t* qp, const bf16_t* kvp, bf16_t* obuf, float* lse, const float* biasG, const int gi, const int rsh, const int G) {
;     ...
;         const int c0 = ((2 * j) % 3) * 4 + w;
;         int sc[5];
; #pragma unroll
;         for (int cc = 0; cc < 5; ++cc) { const int t = c0 + cc; sc[cc] = t >= 12 ? t - 12 : t; }
;         f32x16 p[5];
;         const LAS float* bt = (const LAS float*)(lds + A_BT);
;         const LAS unsigned char* kbase = lds + A_K0 + hi * KCS + r32 * 16;
; #pragma unroll
;         for (int c2 = 0; c2 < 5; c2 += 2) {
;             bf16x8 ka[4], kb[4];
; #pragma unroll
;             for (int d0 = 0; d0 < 4; ++d0) { ka[d0] = *(const LAS bf16x8*)(kbase + 2 * d0 * KCS + sc[c2] * 512); if (c2 + 1 < 5) kb[d0] = *(const LAS bf16x8*)(kbase + 2 * d0 * KCS + sc[c2 + 1 < 5 ? c2 + 1 : c2] * 512); }
; #pragma unroll
;             for (int q = 0; q < 2; ++q) { const int cc = c2 + q; if (cc < 5) { const bool dead = (np == 0) && (w + cc < 4);
;                 const LAS float* bq_ = dead ? bt + 27 - (160 + r32 - 32 * cc - 4 * hi) : bt;
; #pragma unroll
;                 for (int r = 0; r < 16; ++r) p[cc][r] = bq_[160 + r32 - 32 * cc - crow(r, hi)]; } }
;             __builtin_amdgcn_sched_barrier(0);
; #pragma unroll
;             for (int d0 = 0; d0 < 4; ++d0) {
;                 p[c2] = __builtin_amdgcn_mfma_f32_32x32x16_bf16(ka[d0], qr[d0], p[c2], 0, 0, 0);
;                 if (c2 + 1 < 5) p[c2 + 1 < 5 ? c2 + 1 : c2] = __builtin_amdgcn_mfma_f32_32x32x16_bf16(kb[d0], qr[d0], p[c2 + 1 < 5 ? c2 + 1 : c2], 0, 0, 0);
;             }
;             __builtin_amdgcn_sched_barrier(0);
;         }
.LBB0_115:
	s_lshl_b32 s2, s22, 1
	s_mulk_i32 s22, 0xac
	s_lshr_b32 s3, s22, 8
	s_mul_i32 s3, s3, 3
	s_sub_i32 s2, s2, s3
	s_lshl_b32 s2, s2, 2
	s_and_b32 s2, s2, 0xfc
	s_add_i32 s2, s10, s2
	s_add_i32 s3, s2, -12
	s_cmp_gt_i32 s2, 11
	s_cselect_b32 s27, s3, s2
	s_cmp_gt_i32 s2, 10
	s_cselect_b32 s26, -11, 1
	s_add_i32 s26, s26, s2
	s_cmp_gt_i32 s2, 9
	s_cselect_b32 s23, -10, 2
	s_add_i32 s23, s23, s2
	s_cmp_gt_i32 s2, 8
	s_cselect_b32 s22, -9, 3
	s_add_i32 s22, s22, s2
	s_cmp_gt_i32 s2, 7
	s_cselect_b32 s4, -8, 4
	s_add_i32 s4, s4, s2
	v_readlane_b32 s2, v254, 37
	v_lshl_add_u32 v0, s27, 9, v243
	s_and_b64 vcc, s[46:47], s[52:53]
	v_mov_b32_e32 v186, s2
	v_lshl_add_u32 v1, s26, 9, v243
	ds_read_b128 v[32:35], v0 offset:12320
	ds_read_b128 v[36:39], v0 offset:24640
	ds_read_b128 v[40:43], v1 offset:12320
	ds_read_b128 v[44:47], v1 offset:24640
	ds_read_b128 v[48:51], v0
	ds_read_b128 v[52:55], v0 offset:36960
	ds_read_b128 v[56:59], v1
	ds_read_b128 v[60:63], v1 offset:36960
	v_cndmask_b32_e32 v64, v186, v245, vcc
	v_lshlrev_b32_e32 v187, 2, v238
	v_add3_u32 v64, v64, v187, v250
	ds_read2_b32 v[0:1], v64 offset0:160 offset1:159
	ds_read2_b32 v[2:3], v64 offset0:158 offset1:157
	ds_read2_b32 v[4:5], v64 offset0:152 offset1:151
	ds_read2_b32 v[6:7], v64 offset0:150 offset1:149
	ds_read2_b32 v[8:9], v64 offset0:144 offset1:143
	ds_read2_b32 v[10:11], v64 offset0:142 offset1:141
	ds_read2_b32 v[12:13], v64 offset0:136 offset1:135
	ds_read2_b32 v[14:15], v64 offset0:134 offset1:133
	s_and_b64 vcc, s[46:47], s[50:51]
	v_cndmask_b32_e32 v65, v186, v246, vcc
	v_add3_u32 v65, v65, v187, v250
	s_waitcnt lgkmcnt(8)
	ds_read2_b32 v[80:81], v65 offset0:128 offset1:127
	ds_read2_b32 v[82:83], v65 offset0:126 offset1:125
	ds_read2_b32 v[84:85], v65 offset0:120 offset1:119
	ds_read2_b32 v[86:87], v65 offset0:118 offset1:117
	ds_read2_b32 v[88:89], v65 offset0:112 offset1:111
	ds_read2_b32 v[90:91], v65 offset0:110 offset1:109
	ds_read2_b32 v[92:93], v65 offset0:104 offset1:103
	ds_read2_b32 v[94:95], v65 offset0:102 offset1:101
	s_waitcnt lgkmcnt(0)
	v_mfma_f32_32x32x16_bf16 v[0:15], v[48:51], v[28:31], v[0:15]
	s_nop 0
	v_mfma_f32_32x32x16_bf16 v[80:95], v[56:59], v[28:31], v[80:95]
	v_mfma_f32_32x32x16_bf16 v[0:15], v[32:35], v[24:27], v[0:15]
	v_mfma_f32_32x32x16_bf16 v[80:95], v[40:43], v[24:27], v[80:95]
	v_mfma_f32_32x32x16_bf16 v[0:15], v[36:39], v[20:23], v[0:15]
	v_mfma_f32_32x32x16_bf16 v[80:95], v[44:47], v[20:23], v[80:95]
	v_mfma_f32_32x32x16_bf16 v[0:15], v[52:55], v[16:19], v[0:15]
	v_mfma_f32_32x32x16_bf16 v[80:95], v[60:63], v[16:19], v[80:95]
	v_lshl_add_u32 v48, s23, 9, v243
	s_and_b64 vcc, s[46:47], s[0:1]
	v_lshl_add_u32 v49, s22, 9, v243
	ds_read_b128 v[32:35], v48 offset:12320
	ds_read_b128 v[36:39], v48 offset:24640
	ds_read_b128 v[40:43], v49 offset:12320
	ds_read_b128 v[44:47], v49 offset:24640
	ds_read_b128 v[182:185], v48
	ds_read_b128 v[200:203], v48 offset:36960
	ds_read_b128 v[204:207], v49
	ds_read_b128 v[208:211], v49 offset:36960
	v_cndmask_b32_e32 v178, v186, v247, vcc
	v_add3_u32 v178, v178, v187, v250
	ds_read2_b32 v[64:65], v178 offset0:96 offset1:95
	ds_read2_b32 v[66:67], v178 offset0:94 offset1:93
	ds_read2_b32 v[68:69], v178 offset0:88 offset1:87
	ds_read2_b32 v[70:71], v178 offset0:86 offset1:85
	ds_read2_b32 v[72:73], v178 offset0:80 offset1:79
	ds_read2_b32 v[74:75], v178 offset0:78 offset1:77
	ds_read2_b32 v[76:77], v178 offset0:72 offset1:71
	ds_read2_b32 v[78:79], v178 offset0:70 offset1:69
	s_and_b64 vcc, s[46:47], s[42:43]
	v_cndmask_b32_e32 v179, v186, v248, vcc
	v_add3_u32 v179, v179, v187, v250
	s_waitcnt lgkmcnt(8)
	ds_read2_b32 v[48:49], v179 offset0:64 offset1:63
	ds_read2_b32 v[50:51], v179 offset0:62 offset1:61
	ds_read2_b32 v[52:53], v179 offset0:56 offset1:55
	ds_read2_b32 v[54:55], v179 offset0:54 offset1:53
	ds_read2_b32 v[56:57], v179 offset0:48 offset1:47
	ds_read2_b32 v[58:59], v179 offset0:46 offset1:45
	ds_read2_b32 v[60:61], v179 offset0:40 offset1:39
	ds_read2_b32 v[62:63], v179 offset0:38 offset1:37
	s_waitcnt lgkmcnt(0)
	v_mfma_f32_32x32x16_bf16 v[64:79], v[182:185], v[28:31], v[64:79]
	s_nop 0
	v_mfma_f32_32x32x16_bf16 v[48:63], v[204:207], v[28:31], v[48:63]
	v_mfma_f32_32x32x16_bf16 v[64:79], v[32:35], v[24:27], v[64:79]
	v_mfma_f32_32x32x16_bf16 v[48:63], v[40:43], v[24:27], v[48:63]
	v_mfma_f32_32x32x16_bf16 v[64:79], v[36:39], v[20:23], v[64:79]
	v_mfma_f32_32x32x16_bf16 v[48:63], v[44:47], v[20:23], v[48:63]
	v_mfma_f32_32x32x16_bf16 v[64:79], v[200:203], v[16:19], v[64:79]
	v_mfma_f32_32x32x16_bf16 v[48:63], v[208:211], v[16:19], v[48:63]
	v_lshl_add_u32 v32, s4, 9, v243
	s_and_b64 vcc, s[46:47], s[44:45]
	ds_read_b128 v[182:185], v32 offset:12320
	ds_read_b128 v[200:203], v32 offset:24640
	ds_read_b128 v[204:207], v32
	ds_read_b128 v[208:211], v32 offset:36960
	v_cndmask_b32_e32 v178, v186, v249, vcc
	v_add3_u32 v178, v178, v187, v250
	ds_read2_b32 v[32:33], v178 offset0:32 offset1:31
	ds_read2_b32 v[34:35], v178 offset0:30 offset1:29
	ds_read2_b32 v[36:37], v178 offset0:24 offset1:23
	ds_read2_b32 v[38:39], v178 offset0:22 offset1:21
	ds_read2_b32 v[40:41], v178 offset0:16 offset1:15
	ds_read2_b32 v[42:43], v178 offset0:14 offset1:13
	ds_read2_b32 v[44:45], v178 offset0:8 offset1:7
	ds_read2_b32 v[46:47], v178 offset0:6 offset1:5
	s_waitcnt lgkmcnt(0)
; #define LAS __attribute__((address_space(3)))
; __device__ __forceinline__ void attn_phase(LAS unsigned char* lds, const bf16_t* qp, const bf16_t* kvp, bf16_t* obuf, float* lse, const float* biasG, const int gi, const int rsh, const int G) {
;     ...
;                 p[c2] = __builtin_amdgcn_mfma_f32_32x32x16_bf16(ka[d0], qr[d0], p[c2], 0, 0, 0);
;                 if (c2 + 1 < 5) p[c2 + 1 < 5 ? c2 + 1 : c2] = __builtin_amdgcn_mfma_f32_32x32x16_bf16(kb[d0], qr[d0], p[c2 + 1 < 5 ? c2 + 1 : c2], 0, 0, 0);
;             }
;             __builtin_amdgcn_sched_barrier(0);
;         }
;         float mx = p[0][0];
; #pragma unroll
;         for (int cc = 0; cc < 5; ++cc)
; #pragma unroll
;             for (int r = 0; r < 16; ++r) mx = fmaxf(mx, p[cc][r]);
;         mx = fmaxf(mx, __shfl_xor(mx, 32));
;         typedef float f32x2 __attribute__((ext_vector_type(2)));
;         f32x2 l2 = (f32x2){0.f, 0.f};
;     ...
;         ATT_EXP8(0, 0); ATT_EXP8(0, 8);
;         bf16_t* og = obuf + ((size_t)h * M + growq) * 64 + 8 * hi;
;         u32x4 prev[2][2];
;         f32x16 o[2];
; #pragma unroll
;         for (int r = 0; r < 16; ++r) { o[0][r] = 0.f; o[1][r] = 0.f; }
;         const LAS unsigned char* vb = lds + A_V0 + ((lane >> 4) & 1) * 32 + (lane & 3) * 8 + (4 * hi + ((lane & 15) >> 2)) * 64;
; #pragma unroll
;         for (int cc = 0; cc < 5; ++cc)
; #pragma unroll
;             for (int gk = 0; gk < 2; ++gk) {
;                 if (cc == 3 && gk == 0 && gi > 0) {
; #pragma unroll
;                     for (int d0 = 0; d0 < 2; ++d0)
; #pragma unroll
;                         for (int pr = 0; pr < 2; ++pr) prev[d0][pr] = gld<u32x4>(og + 32 * d0 + 16 * pr);
;                 }
;                 if (cc + 1 < 5) ATT_EXP8(cc + 1 < 5 ? cc + 1 : cc, 8 * gk);
;                 u32x4 pw; pw.x = cvt_pk_bf16(p[cc][8 * gk + 0], p[cc][8 * gk + 1]); pw.y = cvt_pk_bf16(p[cc][8 * gk + 2], p[cc][8 * gk + 3]);
;                 pw.z = cvt_pk_bf16(p[cc][8 * gk + 4], p[cc][8 * gk + 5]); pw.w = cvt_pk_bf16(p[cc][8 * gk + 6], p[cc][8 * gk + 7]);
;                 const bf16x8 pa = __builtin_bit_cast(bf16x8, pw);
;                 const LAS unsigned char* vrow = vb + sc[cc] * 2048 + gk * 1024;
; #pragma unroll
;                 for (int d0 = 0; d0 < 2; ++d0) {
;                     const v4i16_t lo = vtr(vrow + d0 * VHS), hh = vtr(vrow + d0 * VHS + 512);
	s_nop 1
	v_mfma_f32_32x32x16_bf16 v[32:47], v[204:207], v[28:31], v[32:47]
	v_mfma_f32_32x32x16_bf16 v[32:47], v[182:185], v[24:27], v[32:47]
	v_mfma_f32_32x32x16_bf16 v[32:47], v[200:203], v[20:23], v[32:47]
	v_mfma_f32_32x32x16_bf16 v[32:47], v[208:211], v[16:19], v[32:47]
	v_max_f32_e32 v16, v1, v1
	v_max_f32_e32 v17, v0, v0
	v_max_f32_e32 v16, v17, v16
	v_max3_f32 v16, v16, v2, v3
	v_max3_f32 v16, v16, v4, v5
	v_max3_f32 v16, v16, v6, v7
	v_max3_f32 v16, v16, v8, v9
	v_max3_f32 v16, v16, v10, v11
	v_max3_f32 v16, v16, v12, v13
	v_max3_f32 v16, v16, v14, v15
	v_max3_f32 v16, v16, v80, v81
	v_max3_f32 v16, v16, v82, v83
	v_max3_f32 v16, v16, v84, v85
	v_max3_f32 v16, v16, v86, v87
	v_max3_f32 v16, v16, v88, v89
	v_max3_f32 v16, v16, v90, v91
	v_max3_f32 v16, v16, v92, v93
	v_max3_f32 v16, v16, v94, v95
	v_max3_f32 v16, v16, v64, v65
	v_max3_f32 v16, v16, v66, v67
	v_max3_f32 v16, v16, v68, v69
	v_max3_f32 v16, v16, v70, v71
	v_max3_f32 v16, v16, v72, v73
	v_max3_f32 v16, v16, v74, v75
	v_max3_f32 v16, v16, v76, v77
	v_max3_f32 v16, v16, v78, v79
	v_max3_f32 v16, v16, v48, v49
	v_max3_f32 v16, v16, v50, v51
	v_max3_f32 v16, v16, v52, v53
	v_max3_f32 v16, v16, v54, v55
	v_max3_f32 v16, v16, v56, v57
	v_max3_f32 v16, v16, v58, v59
	v_max3_f32 v16, v16, v60, v61
	v_max3_f32 v16, v16, v62, v63
	v_max3_f32 v16, v16, v32, v33
	v_max3_f32 v16, v16, v34, v35
	v_max3_f32 v16, v16, v36, v37
	v_max3_f32 v16, v16, v38, v39
	v_and_b32_e32 v18, 64, v233
	v_max3_f32 v16, v16, v40, v41
	v_xor_b32_e32 v17, 32, v233
	v_add_u32_e32 v18, 64, v18
	v_max3_f32 v16, v16, v42, v43
	v_cmp_lt_i32_e32 vcc, v17, v18
	v_max3_f32 v16, v16, v44, v45
	v_max3_f32 v16, v16, v46, v47
	v_cndmask_b32_e32 v17, v233, v17, vcc
	v_lshlrev_b32_e32 v228, 2, v17
	ds_bpermute_b32 v17, v228, v16
	s_lshl_b32 s2, s19, 22
	v_readlane_b32 s3, v255, 21
	s_add_u32 s2, s3, s2
	v_readlane_b32 s3, v255, 22
	s_waitcnt lgkmcnt(0)
	v_max_f32_e32 v17, v17, v17
	v_max_f32_e32 v200, v16, v17
	v_pk_add_f32 v[0:1], v[0:1], v[200:201] op_sel_hi:[1,0] neg_lo:[0,1] neg_hi:[0,1]
	s_addc_u32 s3, s3, 0
	v_exp_f32_e32 v202, v0
	v_exp_f32_e32 v203, v1
	v_pk_add_f32 v[0:1], v[2:3], v[200:201] op_sel_hi:[1,0] neg_lo:[0,1] neg_hi:[0,1]
	v_mov_b32_e32 v191, v96
	v_exp_f32_e32 v204, v0
	v_exp_f32_e32 v205, v1
	v_pk_add_f32 v[0:1], v[4:5], v[200:201] op_sel_hi:[1,0] neg_lo:[0,1] neg_hi:[0,1]
	v_lshl_add_u32 v178, s27, 11, v244
	v_exp_f32_e32 v206, v0
	v_exp_f32_e32 v207, v1
	v_pk_add_f32 v[0:1], v[6:7], v[200:201] op_sel_hi:[1,0] neg_lo:[0,1] neg_hi:[0,1]
	v_add_u32_e32 v179, 0xc080, v178
	v_exp_f32_e32 v208, v0
	v_exp_f32_e32 v209, v1
	v_pk_add_f32 v[0:1], v[8:9], v[200:201] op_sel_hi:[1,0] neg_lo:[0,1] neg_hi:[0,1]
	v_pk_add_f32 v[64:65], v[64:65], v[200:201] op_sel_hi:[1,0] neg_lo:[0,1] neg_hi:[0,1]
	v_exp_f32_e32 v210, v0
	v_exp_f32_e32 v211, v1
	v_pk_add_f32 v[0:1], v[10:11], v[200:201] op_sel_hi:[1,0] neg_lo:[0,1] neg_hi:[0,1]
	s_and_b64 vcc, exec, s[54:55]
	v_exp_f32_e32 v212, v0
	v_exp_f32_e32 v213, v1
	v_pk_add_f32 v[0:1], v[12:13], v[200:201] op_sel_hi:[1,0] neg_lo:[0,1] neg_hi:[0,1]
	s_nop 0
	v_exp_f32_e32 v214, v0
	v_exp_f32_e32 v215, v1
	v_pk_add_f32 v[0:1], v[14:15], v[200:201] op_sel_hi:[1,0] neg_lo:[0,1] neg_hi:[0,1]
	s_nop 0
	v_exp_f32_e32 v216, v0
	v_exp_f32_e32 v217, v1
	v_lshlrev_b64 v[0:1], 7, v[198:199]
	v_lshl_add_u64 v[0:1], s[2:3], 0, v[0:1]
	v_lshl_add_u64 v[198:199], v[0:1], 0, v[190:191]
	v_pk_add_f32 v[0:1], v[80:81], v[200:201] op_sel_hi:[1,0] neg_lo:[0,1] neg_hi:[0,1]
	s_nop 0
	v_exp_f32_e32 v80, v0
	v_exp_f32_e32 v81, v1
	v_pk_add_f32 v[0:1], v[82:83], v[200:201] op_sel_hi:[1,0] neg_lo:[0,1] neg_hi:[0,1]
	s_nop 0
	v_exp_f32_e32 v218, v0
	v_exp_f32_e32 v219, v1
	v_pk_add_f32 v[0:1], v[84:85], v[200:201] op_sel_hi:[1,0] neg_lo:[0,1] neg_hi:[0,1]
	s_nop 0
	v_exp_f32_e32 v84, v0
	v_exp_f32_e32 v85, v1
	v_pk_add_f32 v[0:1], v[86:87], v[200:201] op_sel_hi:[1,0] neg_lo:[0,1] neg_hi:[0,1]
	v_pk_add_f32 v[86:87], v[88:89], v[200:201] op_sel_hi:[1,0] neg_lo:[0,1] neg_hi:[0,1]
	v_exp_f32_e32 v82, v0
	v_exp_f32_e32 v83, v1
	v_cvt_pk_bf16_f32 v0, v202, v203
	v_cvt_pk_bf16_f32 v1, v204, v205
	v_cvt_pk_bf16_f32 v2, v206, v207
	v_cvt_pk_bf16_f32 v3, v208, v209
	ds_read_b64_tr_b16 v[4:5], v178 offset:49280
	ds_read_b64_tr_b16 v[6:7], v178 offset:49792
	s_waitcnt lgkmcnt(0)
; __device__ __forceinline__ unsigned cvt_pk_bf16(float lo, float hi) { unsigned r; asm volatile("v_cvt_pk_bf16_f32 %0, %1, %2" : "=v"(r) : "v"(lo), "v"(hi)); return r; }
; #define LAS __attribute__((address_space(3)))
; __device__ __forceinline__ v4i16_t vtr(const LAS unsigned char* p) { return __builtin_amdgcn_ds_read_tr16_b64_v4i16((LAS v4i16_t*)p); }
; #define ATT_EXP8(cc_, r0_) do { _Pragma("unroll") for (int r = (r0_); r < (r0_) + 8; r += 2) { \
;                 const f32x2 d_ = (f32x2){p[cc_][r], p[cc_][r + 1]} - mx; f32x2 e_; e_.x = __builtin_amdgcn_exp2f(d_.x); e_.y = __builtin_amdgcn_exp2f(d_.y); \
;                 p[cc_][r] = e_.x; p[cc_][r + 1] = e_.y; l2 += e_; } } while (0)
; __device__ __forceinline__ void attn_phase(LAS unsigned char* lds, const bf16_t* qp, const bf16_t* kvp, bf16_t* obuf, float* lse, const float* biasG, const int gi, const int rsh, const int G) {
;     ...
;         for (int cc = 0; cc < 5; ++cc)
; #pragma unroll
;             for (int gk = 0; gk < 2; ++gk) {
;                 if (cc == 3 && gk == 0 && gi > 0) {
; #pragma unroll
;                     for (int d0 = 0; d0 < 2; ++d0)
; #pragma unroll
;                         for (int pr = 0; pr < 2; ++pr) prev[d0][pr] = gld<u32x4>(og + 32 * d0 + 16 * pr);
;                 }
;                 if (cc + 1 < 5) ATT_EXP8(cc + 1 < 5 ? cc + 1 : cc, 8 * gk);
;                 u32x4 pw; pw.x = cvt_pk_bf16(p[cc][8 * gk + 0], p[cc][8 * gk + 1]); pw.y = cvt_pk_bf16(p[cc][8 * gk + 2], p[cc][8 * gk + 3]);
;                 pw.z = cvt_pk_bf16(p[cc][8 * gk + 4], p[cc][8 * gk + 5]); pw.w = cvt_pk_bf16(p[cc][8 * gk + 6], p[cc][8 * gk + 7]);
;                 const bf16x8 pa = __builtin_bit_cast(bf16x8, pw);
;                 const LAS unsigned char* vrow = vb + sc[cc] * 2048 + gk * 1024;
; #pragma unroll
;                 for (int d0 = 0; d0 < 2; ++d0) {
;                     const v4i16_t lo = vtr(vrow + d0 * VHS), hh = vtr(vrow + d0 * VHS + 512);
;                     const bf16x8 vf = (bf16x8){lo[0], lo[1], lo[2], lo[3], hh[0], hh[1], hh[2], hh[3]};
;                     o[d0] = __builtin_amdgcn_mfma_f32_32x32x16_bf16(vf, pa, o[d0], 0, 0, 0);
;                 }
;             }
	v_mfma_f32_32x32x16_bf16 v[16:31], v[4:7], v[0:3], 0
	ds_read_b64_tr_b16 v[4:5], v179 offset:24640
	ds_read_b64_tr_b16 v[6:7], v179 offset:25152
	v_exp_f32_e32 v220, v86
	v_exp_f32_e32 v221, v87
	v_pk_add_f32 v[86:87], v[90:91], v[200:201] op_sel_hi:[1,0] neg_lo:[0,1] neg_hi:[0,1]
	s_nop 0
	v_exp_f32_e32 v90, v86
	v_exp_f32_e32 v91, v87
	v_pk_add_f32 v[86:87], v[92:93], v[200:201] op_sel_hi:[1,0] neg_lo:[0,1] neg_hi:[0,1]
	v_cvt_pk_bf16_f32 v92, v210, v211
	v_cvt_pk_bf16_f32 v93, v212, v213
	s_waitcnt lgkmcnt(0)
	v_mfma_f32_32x32x16_bf16 v[0:15], v[4:7], v[0:3], 0
	v_exp_f32_e32 v88, v86
	v_exp_f32_e32 v89, v87
	v_pk_add_f32 v[86:87], v[94:95], v[200:201] op_sel_hi:[1,0] neg_lo:[0,1] neg_hi:[0,1]
	v_cvt_pk_bf16_f32 v94, v214, v215
	v_cvt_pk_bf16_f32 v95, v216, v217
	ds_read_b64_tr_b16 v[182:183], v178 offset:50304
	ds_read_b64_tr_b16 v[184:185], v178 offset:50816
	v_lshl_add_u32 v178, s26, 11, v244
	s_waitcnt lgkmcnt(0)
	v_mfma_f32_32x32x16_bf16 v[16:31], v[182:185], v[92:95], v[16:31]
	ds_read_b64_tr_b16 v[182:183], v179 offset:25664
	ds_read_b64_tr_b16 v[184:185], v179 offset:26176
	v_add_u32_e32 v179, 0xc080, v178
	v_exp_f32_e32 v86, v86
	v_exp_f32_e32 v87, v87
	s_waitcnt lgkmcnt(0)
	v_mfma_f32_32x32x16_bf16 v[0:15], v[182:185], v[92:95], v[0:15]
	v_exp_f32_e32 v94, v64
	v_exp_f32_e32 v95, v65
	v_pk_add_f32 v[64:65], v[66:67], v[200:201] op_sel_hi:[1,0] neg_lo:[0,1] neg_hi:[0,1]
	s_nop 0
	v_exp_f32_e32 v92, v64
	v_exp_f32_e32 v93, v65
	v_pk_add_f32 v[64:65], v[68:69], v[200:201] op_sel_hi:[1,0] neg_lo:[0,1] neg_hi:[0,1]
	v_cvt_pk_bf16_f32 v68, v80, v81
	v_cvt_pk_bf16_f32 v69, v218, v219
	s_nop 0
	v_exp_f32_e32 v66, v64
	v_exp_f32_e32 v67, v65
	v_pk_add_f32 v[64:65], v[70:71], v[200:201] op_sel_hi:[1,0] neg_lo:[0,1] neg_hi:[0,1]
	v_cvt_pk_bf16_f32 v70, v84, v85
	v_cvt_pk_bf16_f32 v71, v82, v83
	ds_read_b64_tr_b16 v[182:183], v178 offset:49280
	ds_read_b64_tr_b16 v[184:185], v178 offset:49792
	s_waitcnt lgkmcnt(0)
	v_mfma_f32_32x32x16_bf16 v[16:31], v[182:185], v[68:71], v[16:31]
	ds_read_b64_tr_b16 v[182:183], v179 offset:24640
	ds_read_b64_tr_b16 v[184:185], v179 offset:25152
	v_exp_f32_e32 v64, v64
	v_exp_f32_e32 v65, v65
	s_waitcnt lgkmcnt(0)
	v_mfma_f32_32x32x16_bf16 v[0:15], v[182:185], v[68:71], v[0:15]
	v_add_f32_e64 v68, v72, -v200
	v_add_f32_e64 v69, v73, -v200
	v_exp_f32_e32 v222, v68
	v_exp_f32_e32 v223, v69
	v_pk_add_f32 v[68:69], v[74:75], v[200:201] op_sel_hi:[1,0] neg_lo:[0,1] neg_hi:[0,1]
	v_cvt_pk_bf16_f32 v74, v220, v221
	v_cvt_pk_bf16_f32 v75, v90, v91
	s_nop 0
	v_exp_f32_e32 v72, v68
	v_exp_f32_e32 v73, v69
	v_pk_add_f32 v[68:69], v[76:77], v[200:201] op_sel_hi:[1,0] neg_lo:[0,1] neg_hi:[0,1]
	v_cvt_pk_bf16_f32 v76, v88, v89
	v_cvt_pk_bf16_f32 v77, v86, v87
	ds_read_b64_tr_b16 v[182:183], v178 offset:50304
	ds_read_b64_tr_b16 v[184:185], v178 offset:50816
	s_waitcnt lgkmcnt(0)
	v_mfma_f32_32x32x16_bf16 v[16:31], v[182:185], v[74:77], v[16:31]
	ds_read_b64_tr_b16 v[182:183], v179 offset:25664
	ds_read_b64_tr_b16 v[184:185], v179 offset:26176
	v_exp_f32_e32 v70, v68
	v_exp_f32_e32 v71, v69
	v_pk_add_f32 v[68:69], v[78:79], v[200:201] op_sel_hi:[1,0] neg_lo:[0,1] neg_hi:[0,1]
	v_lshl_add_u32 v78, s23, 11, v244
	v_add_u32_e32 v79, 0xc080, v78
	v_exp_f32_e32 v68, v68
	s_waitcnt lgkmcnt(0)
	v_mfma_f32_32x32x16_bf16 v[0:15], v[182:185], v[74:77], v[0:15]
	v_cvt_pk_bf16_f32 v74, v94, v95
	v_cvt_pk_bf16_f32 v75, v92, v93
	v_cvt_pk_bf16_f32 v76, v66, v67
	v_cvt_pk_bf16_f32 v77, v64, v65
	ds_read_b64_tr_b16 v[182:183], v78 offset:49280
	ds_read_b64_tr_b16 v[184:185], v78 offset:49792
	v_exp_f32_e32 v69, v69
	s_waitcnt lgkmcnt(0)
	v_mfma_f32_32x32x16_bf16 v[16:31], v[182:185], v[74:77], v[16:31]
	ds_read_b64_tr_b16 v[182:183], v79 offset:24640
	ds_read_b64_tr_b16 v[184:185], v79 offset:25152
	s_waitcnt lgkmcnt(0)
	v_mfma_f32_32x32x16_bf16 v[0:15], v[182:185], v[74:77], v[0:15]
	v_cvt_pk_bf16_f32 v74, v222, v223
	v_cvt_pk_bf16_f32 v75, v72, v73
	v_cvt_pk_bf16_f32 v76, v70, v71
	v_cvt_pk_bf16_f32 v77, v68, v69
	ds_read_b64_tr_b16 v[182:183], v78 offset:50304
	ds_read_b64_tr_b16 v[184:185], v78 offset:50816
	s_waitcnt lgkmcnt(0)
	v_mfma_f32_32x32x16_bf16 v[16:31], v[182:185], v[74:77], v[16:31]
	ds_read_b64_tr_b16 v[182:183], v79 offset:25664
	ds_read_b64_tr_b16 v[184:185], v79 offset:26176
	s_waitcnt lgkmcnt(0)
	v_mfma_f32_32x32x16_bf16 v[0:15], v[182:185], v[74:77], v[0:15]
	s_cbranch_vccnz .LBB0_117
	global_load_dwordx4 v[158:161], v[198:199], off
	global_load_dwordx4 v[154:157], v[198:199], off offset:32
	global_load_dwordx4 v[150:153], v[198:199], off offset:64
	global_load_dwordx4 v[146:149], v[198:199], off offset:96
